# in-proj copy workers stop on a tile-progress counter (about one tile before the phase end) instead of at the first finished GEMM workgroup
# baseline (speedup 1.0000x reference)
.LBB0_281:
	s_and_saveexec_b64 s[20:21], s[36:37]
	s_cbranch_execz .LBB0_289
	s_and_b64 vcc, exec, s[8:9]
	s_mov_b64 s[22:23], s[16:17]
	s_cbranch_vccnz .LBB0_284
	global_load_dword v0, v129, s[18:19] sc1
	s_waitcnt vmcnt(0)
	v_cmp_gt_i32_e32 vcc, 0x4e2, v0
	s_mov_b64 s[22:23], vcc

.Lproj_keep:
	s_and_saveexec_b64 s[6:7], s[36:37]
	s_cbranch_execz .Lip_noatom
	v_mov_b32_e32 v196, 0x6330000
	v_mov_b32_e32 v197, 1
	global_atomic_add v196, v197, s[40:41] offset:3204
.Lip_noatom:
	s_mov_b64 exec, s[6:7]
	s_cmp_gt_u32 s8, 19
	s_cselect_b64 s[52:53], -1, 0
	s_and_b64 s[6:7], s[52:53], exec
	s_cselect_b32 s94, s84, 0x2cc0000
	s_cselect_b32 s93, s85, 0x24c0000
	s_lshl_b32 s45, s8, 8
	s_cmp_eq_u32 s8, 24
	s_cselect_b64 s[50:51], -1, 0
	s_and_b64 s[6:7], s[52:53], exec
	s_cselect_b32 s54, s86, 0xfffff000
	s_ashr_i32 s6, s95, 1
	v_or_b32_e32 v150, s95, v137
	s_and_b32 s97, s6, 0xfffff800
	s_ashr_i32 s6, s95, 9
	v_cndmask_b32_e64 v134, 0, 1, s[56:57]
	v_or_b32_e32 v148, s45, v136
	s_addk_i32 s97, 0xf800
	s_and_b32 s96, s6, -8
	v_cmp_gt_i32_e32 vcc, s87, v150
	v_cmp_ne_u32_e64 s[6:7], 1, v134
	s_and_saveexec_b64 s[58:59], vcc
	s_cbranch_execz .LBB0_348
	v_ashrrev_i32_e32 v151, 31, v150
	v_lshl_add_u64 v[152:153], v[150:151], 2, s[22:23]
	global_load_dword v152, v[152:153], off
	s_and_b64 vcc, exec, s[6:7]
	v_mov_b64_e32 v[154:155], 0
	s_cbranch_vccnz .LBB0_324
	v_cmp_lt_i32_e32 vcc, s88, v150
	s_and_saveexec_b64 s[8:9], vcc
	s_xor_b64 s[8:9], exec, s[8:9]
	v_lshlrev_b32_e32 v134, 9, v150
	s_lshl_b32 s55, s94, 2
	v_and_b32_e32 v134, 0x7fff9800, v134
	s_add_u32 s60, s18, s55
	v_add_u32_e32 v134, v134, v162
	s_addc_u32 s61, s19, 0
	v_lshlrev_b64 v[154:155], 12, v[134:135]
	v_lshl_add_u64 v[154:155], s[60:61], 0, v[154:155]
	s_andn2_saveexec_b64 s[8:9], s[8:9]
	s_cbranch_execz .LBB0_323
	v_and_b32_e32 v134, 0xfcf, v150
	v_add_u32_e32 v154, s97, v134
	s_lshl_b32 s55, s93, 2
	v_ashrrev_i32_e32 v155, 31, v154
	s_add_u32 s60, s18, s55
	v_lshlrev_b64 v[154:155], 12, v[154:155]
	s_addc_u32 s61, s19, 0
	v_lshl_add_u64 v[154:155], s[60:61], 0, v[154:155]
	v_cmp_lt_u32_e32 vcc, s89, v134
	s_nop 1
	v_cndmask_b32_e32 v155, 0, v155, vcc
	v_cndmask_b32_e32 v154, 0, v154, vcc
